# first-barrier census: 16 sc1 counter loads issued back-to-back with one vmcnt(0) instead of serialized waits
# speedup vs baseline: 1.0008x; 1.0008x over previous
.LBB0_133:
	v_readlane_b32 s6, v249, 7
	v_readlane_b32 s7, v249, 8
	global_load_dword v2, v16, s[96:97] sc1
	s_waitcnt lgkmcnt(0)
	global_load_dword v0, v16, s[50:51] sc1
	global_load_dword v1, v16, s[52:53] sc1
	s_mov_b64 s[24:25], -1
	s_mov_b64 s[26:27], -1
	global_load_dword v3, v16, s[6:7] sc1
	v_readlane_b32 s6, v249, 9
	v_readlane_b32 s7, v249, 10
	s_nop 4
	global_load_dword v4, v16, s[6:7] sc1
	v_readlane_b32 s6, v249, 11
	v_readlane_b32 s7, v249, 12
	s_nop 4
	global_load_dword v5, v16, s[6:7] sc1
	v_readlane_b32 s6, v249, 13
	v_readlane_b32 s7, v249, 14
	s_nop 4
	global_load_dword v6, v16, s[6:7] sc1
	v_readlane_b32 s6, v249, 15
	v_readlane_b32 s7, v249, 16
	s_nop 4
	global_load_dword v7, v16, s[6:7] sc1
	v_readlane_b32 s6, v249, 17
	v_readlane_b32 s7, v249, 18
	s_nop 4
	global_load_dword v8, v16, s[6:7] sc1
	v_readlane_b32 s6, v249, 19
	v_readlane_b32 s7, v249, 20
	s_nop 4
	global_load_dword v9, v16, s[6:7] sc1
	v_readlane_b32 s6, v249, 21
	v_readlane_b32 s7, v249, 22
	s_nop 4
	global_load_dword v10, v16, s[6:7] sc1
	v_readlane_b32 s6, v249, 23
	v_readlane_b32 s7, v249, 24
	s_nop 4
	global_load_dword v11, v16, s[6:7] sc1
	v_readlane_b32 s6, v249, 25
	v_readlane_b32 s7, v249, 26
	s_nop 4
	global_load_dword v12, v16, s[6:7] sc1
	v_readlane_b32 s6, v249, 27
	v_readlane_b32 s7, v249, 28
	s_nop 4
	global_load_dword v13, v16, s[6:7] sc1
	v_readlane_b32 s6, v249, 29
	v_readlane_b32 s7, v249, 30
	s_nop 4
	global_load_dword v14, v16, s[6:7] sc1
	v_readlane_b32 s6, v249, 31
	v_readlane_b32 s7, v249, 32
	s_nop 4
	global_load_dword v15, v16, s[6:7] sc1
	s_waitcnt vmcnt(0)
	v_add_u32_e32 v17, v0, v2
	v_add3_u32 v17, v17, v1, v3
	v_add3_u32 v17, v17, v4, v5
	v_add3_u32 v17, v17, v6, v7
	v_add3_u32 v17, v17, v8, v9
	v_add3_u32 v17, v17, v10, v11
	v_add3_u32 v17, v17, v12, v13
	v_add3_u32 v17, v17, v14, v15
	v_cmp_eq_u32_e32 vcc, s72, v17
	s_cbranch_vccnz .LBB0_132
	s_and_b32 s5, s4, 0xff
	s_cmp_eq_u32 s5, 0
	s_mov_b64 s[28:29], -1
	s_sleep 1
	s_cbranch_scc1 .LBB0_137
	s_and_b64 vcc, exec, s[28:29]
	s_cbranch_vccz .LBB0_132
